# readout phase: all 12 streaming loads of a row issued at the top of the row (was 4 serialized groups of 3), counted waits recomputed
# speedup vs baseline: 1.0067x; 1.0061x over previous
; #define GAS __attribute__((address_space(1)))
; __device__ __forceinline__ unsigned pk2(float lo, float hi) { return pg8::cvt_pk_bf16(lo, hi); }
; __device__ __forceinline__ void readout_phase(int gw, int NGW, int lane_in, const bf16* OFW, const bf16* OBW, const bf16* HG, const float* onorm, bf16* XN) {
;     ...
;     for (int it = 0;; ++it) { const int r = row_of(it, gw, NGW, MALL); if (r < 0) break; if (r % SB < 256) continue;
; #pragma unroll
;         for (int j = 0; j < 4; ++j) { const int col = 8 * lane + 512 * j;
;             const size_t ho = ((size_t)(col >> 7) * MALL + r) * 128 + (col & 127);
;             const v4u a = __builtin_nontemporal_load((const GAS v4u*)(OFW + ho)), bq = __builtin_nontemporal_load((const GAS v4u*)(OBW + ho)), gq = __builtin_nontemporal_load((const GAS v4u*)(HG + (size_t)64 * MALL * 128 + ho));
;             float o[8], sg[8];
; #pragma unroll
;             for (int q = 0; q < 4; ++q) { o[2 * q] = bf2f(a[q] & 0xffffu) + bf2f(bq[q] & 0xffffu); o[2 * q + 1] = bf2f(a[q] >> 16) + bf2f(bq[q] >> 16); sg[2 * q] = bf2f(gq[q] & 0xffffu); sg[2 * q + 1] = bf2f(gq[q] >> 16); }
;             float ss = 0.f;
; #pragma unroll
;             for (int e = 0; e < 8; ++e) ss += o[e] * o[e];
;             ss += __shfl_xor(ss, 1); ss += __shfl_xor(ss, 2); ss += __shfl_xor(ss, 4); ss += __shfl_xor(ss, 8);
;             const float rs = 1.f / sqrtf(ss * (1.f / 128.f) + EPS);
;             v4u w;
; #pragma unroll
;             for (int q = 0; q < 4; ++q) w[q] = pk2(o[2 * q] * rs * gn[2 * q] * sg[2 * q], o[2 * q + 1] * rs * gn[2 * q + 1] * sg[2 * q + 1]);
;             *(GAS v4u*)(XN + (size_t)r * 2048 + col) = w; }
.LBB0_2659:
	s_cmp_lt_i32 s28, 0
	s_mov_b32 s8, 5
	s_cbranch_scc1 .LBB0_2662
	s_mul_hi_u32 s4, s28, 0x3e0f83e1
	s_lshr_b32 s4, s4, 11
	s_mulk_i32 s4, 0x2100
	s_sub_i32 s4, s28, s4
	s_cmpk_lt_u32 s4, 0x100
	s_mov_b32 s8, 7
	s_cbranch_scc1 .LBB0_2662
	v_add_u32_e32 v12, s28, v18
	v_lshlrev_b64 v[8:9], 8, v[12:13]
	v_or_b32_e32 v8, v8, v22
	v_lshl_add_u64 v[10:11], s[0:1], 0, v[8:9]
	v_lshl_add_u64 v[16:17], s[20:21], 0, v[8:9]
	global_load_dwordx4 v[26:29], v[10:11], off nt
	global_load_dwordx4 v[30:33], v[16:17], off nt
	v_lshl_add_u64 v[8:9], s[26:27], 0, v[8:9]
	global_load_dwordx4 v[8:11], v[8:9], off nt
	v_add_u32_e32 v98, s28, v19
	v_mov_b32_e32 v99, v13
	v_lshlrev_b64 v[98:99], 8, v[98:99]
	v_or_b32_e32 v98, v98, v22
	v_lshl_add_u64 v[60:61], s[0:1], 0, v[98:99]
	v_lshl_add_u64 v[64:65], s[20:21], 0, v[98:99]
	v_lshl_add_u64 v[68:69], s[26:27], 0, v[98:99]
	global_load_dwordx4 v[60:63], v[60:61], off nt
	global_load_dwordx4 v[64:67], v[64:65], off nt
	global_load_dwordx4 v[68:71], v[68:69], off nt
	v_add_u32_e32 v98, s28, v20
	v_mov_b32_e32 v99, v13
	v_lshlrev_b64 v[98:99], 8, v[98:99]
	v_or_b32_e32 v98, v98, v22
	v_lshl_add_u64 v[72:73], s[0:1], 0, v[98:99]
	v_lshl_add_u64 v[76:77], s[20:21], 0, v[98:99]
	v_lshl_add_u64 v[80:81], s[26:27], 0, v[98:99]
	global_load_dwordx4 v[72:75], v[72:73], off nt
	global_load_dwordx4 v[76:79], v[76:77], off nt
	global_load_dwordx4 v[80:83], v[80:81], off nt
	v_add_u32_e32 v98, s28, v21
	v_mov_b32_e32 v99, v13
	v_lshlrev_b64 v[98:99], 8, v[98:99]
	v_or_b32_e32 v98, v98, v22
	v_lshl_add_u64 v[84:85], s[0:1], 0, v[98:99]
	v_lshl_add_u64 v[88:89], s[20:21], 0, v[98:99]
	v_lshl_add_u64 v[92:93], s[26:27], 0, v[98:99]
	global_load_dwordx4 v[84:87], v[84:85], off nt
	global_load_dwordx4 v[88:91], v[88:89], off nt
	global_load_dwordx4 v[92:95], v[92:93], off nt
	v_cmp_lt_i32_e32 vcc, v188, v185
	s_lshl_b64 s[34:35], s[28:29], 12
	s_mov_b32 s8, 0
	v_cndmask_b32_e32 v12, v184, v188, vcc
	s_waitcnt vmcnt(20)
	v_lshlrev_b32_e32 v25, 2, v12
	v_cmp_lt_i32_e32 vcc, v189, v185
	s_waitcnt vmcnt(11)
	v_lshlrev_b32_e32 v12, 16, v26
	s_waitcnt vmcnt(10)
	v_lshlrev_b32_e32 v34, 16, v30
	v_and_b32_e32 v30, 0xffff0000, v30
	v_and_b32_e32 v26, 0xffff0000, v26
	v_add_f32_e32 v41, v34, v12
	v_lshlrev_b32_e32 v35, 16, v27
	v_lshlrev_b32_e32 v36, 16, v31
	v_add_f32_e32 v42, v30, v26
	v_mul_f32_e32 v12, v41, v41
	v_and_b32_e32 v31, 0xffff0000, v31
	v_and_b32_e32 v27, 0xffff0000, v27
	v_add_f32_e32 v36, v36, v35
	v_fmac_f32_e32 v12, v42, v42
	v_lshlrev_b32_e32 v37, 16, v28
	v_lshlrev_b32_e32 v38, 16, v32
	v_add_f32_e32 v43, v31, v27
	v_fmac_f32_e32 v12, v36, v36
	v_and_b32_e32 v32, 0xffff0000, v32
	v_and_b32_e32 v28, 0xffff0000, v28
	v_add_f32_e32 v37, v38, v37
	v_fmac_f32_e32 v12, v43, v43
	v_lshlrev_b32_e32 v39, 16, v29
	v_lshlrev_b32_e32 v40, 16, v33
	v_add_f32_e32 v38, v32, v28
	v_fmac_f32_e32 v12, v37, v37
	v_and_b32_e32 v33, 0xffff0000, v33
	v_and_b32_e32 v29, 0xffff0000, v29
	v_add_f32_e32 v39, v40, v39
	v_fmac_f32_e32 v12, v38, v38
	v_add_f32_e32 v29, v33, v29
	v_fmac_f32_e32 v12, v39, v39
	v_fmac_f32_e32 v12, v29, v29
	ds_bpermute_b32 v26, v25, v12
	v_cndmask_b32_e32 v16, v184, v189, vcc
	v_lshlrev_b32_e32 v27, 2, v16
	v_cmp_lt_i32_e32 vcc, v187, v185
	s_waitcnt vmcnt(9)
	v_lshlrev_b32_e32 v45, 16, v9
	s_waitcnt lgkmcnt(0)
	v_add_f32_e32 v31, v12, v26
	ds_bpermute_b32 v32, v27, v31
	v_cndmask_b32_e32 v17, v184, v187, vcc
	v_lshlrev_b32_e32 v28, 2, v17
	v_cmp_lt_i32_e32 vcc, v186, v185
	v_add_u32_e32 v12, s28, v19
	s_waitcnt lgkmcnt(0)
	v_add_f32_e32 v40, v31, v32
	ds_bpermute_b32 v44, v28, v40
	v_cndmask_b32_e32 v30, v184, v186, vcc
	v_lshlrev_b32_e32 v26, 2, v30
	v_lshlrev_b64 v[34:35], 8, v[12:13]
	v_and_b32_e32 v9, 0xffff0000, v9
	s_waitcnt lgkmcnt(0)
	v_add_f32_e32 v12, v40, v44
	ds_bpermute_b32 v40, v26, v12
	v_lshlrev_b32_e32 v44, 16, v8
	v_and_b32_e32 v8, 0xffff0000, v8
	v_lshlrev_b32_e32 v46, 16, v10
	v_and_b32_e32 v10, 0xffff0000, v10
	s_waitcnt lgkmcnt(0)
	v_add_f32_e32 v12, v12, v40
	v_fmamk_f32 v12, v12, 0x3c000000, v23
	v_mul_f32_e32 v40, 0x4f800000, v12
	v_cmp_gt_f32_e32 vcc, s3, v12
	v_lshlrev_b32_e32 v47, 16, v11
	v_and_b32_e32 v11, 0xffff0000, v11
	v_cndmask_b32_e32 v12, v12, v40, vcc
	v_sqrt_f32_e32 v40, v12
	v_lshl_add_u64 v[16:17], v[14:15], 0, s[34:35]
	v_or_b32_e32 v34, v34, v22
	v_lshl_add_u64 v[30:31], s[0:1], 0, v[34:35]
	v_add_u32_e32 v48, -1, v40
	v_add_u32_e32 v49, 1, v40
	v_fma_f32 v50, -v48, v40, v12
	v_fma_f32 v51, -v49, v40, v12
	v_cmp_ge_f32_e64 s[38:39], 0, v50
	v_lshl_add_u64 v[32:33], s[20:21], 0, v[34:35]
	v_lshl_add_u64 v[34:35], s[26:27], 0, v[34:35]
	v_cndmask_b32_e64 v40, v40, v48, s[38:39]
	v_cmp_lt_f32_e64 s[38:39], 0, v51
	s_nop 1
	v_cndmask_b32_e64 v40, v40, v49, s[38:39]
	v_mul_f32_e32 v48, 0x37800000, v40
	v_cndmask_b32_e32 v40, v40, v48, vcc
	v_cmp_class_f32_e32 vcc, v12, v24
	s_nop 1
	v_cndmask_b32_e32 v12, v40, v12, vcc
	v_div_scale_f32 v40, s[4:5], v12, v12, 1.0
	v_rcp_f32_e32 v48, v40
	v_div_scale_f32 v49, vcc, 1.0, v12, 1.0
	v_fma_f32 v50, -v40, v48, 1.0
	v_fmac_f32_e32 v48, v50, v48
	v_mul_f32_e32 v50, v49, v48
	v_fma_f32 v51, -v40, v50, v49
	v_fmac_f32_e32 v50, v51, v48
	v_fma_f32 v40, -v40, v50, v49
	v_div_fmas_f32 v40, v40, v48, v50
	v_div_fixup_f32 v12, v40, v12, 1.0
	v_mul_f32_e32 v40, v41, v12
	v_mul_f32_e32 v41, v42, v12
	v_mul_f32_e32 v36, v36, v12
	v_mul_f32_e32 v42, v43, v12
	v_mul_f32_e32 v37, v37, v12
	v_mul_f32_e32 v38, v38, v12
	v_mul_f32_e32 v39, v39, v12
	v_mul_f32_e32 v12, v29, v12
	v_mul_f32_e32 v29, v0, v40
	v_mul_f32_e32 v40, v1, v41
	v_mul_f32_e32 v41, v3, v42
	v_mul_f32_e32 v38, v5, v38
	v_mul_f32_e32 v12, v7, v12
	v_mul_f32_e32 v36, v2, v36
	v_mul_f32_e32 v37, v4, v37
	v_mul_f32_e32 v39, v6, v39
	v_mul_f32_e32 v8, v40, v8
	v_mul_f32_e32 v9, v41, v9
	v_mul_f32_e32 v10, v38, v10
	v_mul_f32_e32 v11, v12, v11
	v_mul_f32_e32 v29, v29, v44
	v_mul_f32_e32 v36, v36, v45
	v_mul_f32_e32 v37, v37, v46
	v_mul_f32_e32 v38, v39, v47
	v_cvt_pk_bf16_f32 v8, v29, v8
	v_cvt_pk_bf16_f32 v9, v36, v9
	v_cvt_pk_bf16_f32 v10, v37, v10
	v_cvt_pk_bf16_f32 v11, v38, v11
	global_store_dwordx4 v[16:17], v[8:11], off

; #define GAS __attribute__((address_space(1)))
; __device__ __forceinline__ void readout_phase(int gw, int NGW, int lane_in, const bf16* OFW, const bf16* OBW, const bf16* HG, const float* onorm, bf16* XN) {
;     ...
;             const v4u a = __builtin_nontemporal_load((const GAS v4u*)(OFW + ho)), bq = __builtin_nontemporal_load((const GAS v4u*)(OBW + ho)), gq = __builtin_nontemporal_load((const GAS v4u*)(HG + (size_t)64 * MALL * 128 + ho));
	s_nop 0

; __device__ __forceinline__ void readout_phase(int gw, int NGW, int lane_in, const bf16* OFW, const bf16* OBW, const bf16* HG, const float* onorm, bf16* XN) {
;     ...
;             for (int q = 0; q < 4; ++q) { o[2 * q] = bf2f(a[q] & 0xffffu) + bf2f(bq[q] & 0xffffu); o[2 * q + 1] = bf2f(a[q] >> 16) + bf2f(bq[q] >> 16); sg[2 * q] = bf2f(gq[q] & 0xffffu); sg[2 * q + 1] = bf2f(gq[q] >> 16); }
	s_waitcnt vmcnt(9)
	v_lshlrev_b32_e32 v12, 16, v60

; #define GAS __attribute__((address_space(1)))
; __device__ __forceinline__ unsigned pk2(float lo, float hi) { return pg8::cvt_pk_bf16(lo, hi); }
; __device__ __forceinline__ void readout_phase(int gw, int NGW, int lane_in, const bf16* OFW, const bf16* OBW, const bf16* HG, const float* onorm, bf16* XN) {
;     ...
;             for (int q = 0; q < 4; ++q) { o[2 * q] = bf2f(a[q] & 0xffffu) + bf2f(bq[q] & 0xffffu); o[2 * q + 1] = bf2f(a[q] >> 16) + bf2f(bq[q] >> 16); sg[2 * q] = bf2f(gq[q] & 0xffffu); sg[2 * q + 1] = bf2f(gq[q] >> 16); }
;             float ss = 0.f;
; #pragma unroll
;             for (int e = 0; e < 8; ++e) ss += o[e] * o[e];
;             ss += __shfl_xor(ss, 1); ss += __shfl_xor(ss, 2); ss += __shfl_xor(ss, 4); ss += __shfl_xor(ss, 8);
;             const float rs = 1.f / sqrtf(ss * (1.f / 128.f) + EPS);
;             v4u w;
; #pragma unroll
;             for (int q = 0; q < 4; ++q) w[q] = pk2(o[2 * q] * rs * gn[2 * q] * sg[2 * q], o[2 * q + 1] * rs * gn[2 * q + 1] * sg[2 * q + 1]);
;             *(GAS v4u*)(XN + (size_t)r * 2048 + col) = w; }
	s_waitcnt vmcnt(8)
	v_lshlrev_b32_e32 v29, 16, v64
	v_and_b32_e32 v30, 0xffff0000, v64
	v_and_b32_e32 v8, 0xffff0000, v60
	v_add_f32_e32 v29, v29, v12
	v_lshlrev_b32_e32 v38, 16, v61
	v_lshlrev_b32_e32 v39, 16, v65
	v_add_f32_e32 v8, v30, v8
	v_mul_f32_e32 v12, v29, v29
	v_and_b32_e32 v31, 0xffff0000, v65
	v_and_b32_e32 v9, 0xffff0000, v61
	v_add_f32_e32 v44, v39, v38
	v_fmac_f32_e32 v12, v8, v8
	v_lshlrev_b32_e32 v40, 16, v62
	v_lshlrev_b32_e32 v41, 16, v66
	v_add_f32_e32 v9, v31, v9
	v_fmac_f32_e32 v12, v44, v44
	v_and_b32_e32 v32, 0xffff0000, v66
	v_and_b32_e32 v10, 0xffff0000, v62
	v_add_f32_e32 v40, v41, v40
	v_fmac_f32_e32 v12, v9, v9
	v_lshlrev_b32_e32 v42, 16, v63
	v_lshlrev_b32_e32 v43, 16, v67
	v_add_f32_e32 v10, v32, v10
	v_fmac_f32_e32 v12, v40, v40
	v_and_b32_e32 v33, 0xffff0000, v67
	v_and_b32_e32 v11, 0xffff0000, v63
	v_add_f32_e32 v41, v43, v42
	v_fmac_f32_e32 v12, v10, v10
	v_add_f32_e32 v11, v33, v11
	v_fmac_f32_e32 v12, v41, v41
	v_fmac_f32_e32 v12, v11, v11
	ds_bpermute_b32 v30, v25, v12
	s_waitcnt lgkmcnt(0)
	v_add_f32_e32 v30, v12, v30
	ds_bpermute_b32 v31, v27, v30
	v_add_u32_e32 v12, s28, v20
	v_lshlrev_b64 v[38:39], 8, v[12:13]
	v_or_b32_e32 v38, v38, v22
	v_lshl_add_u64 v[32:33], s[20:21], 0, v[38:39]
	s_waitcnt lgkmcnt(0)
	v_add_f32_e32 v42, v30, v31
	ds_bpermute_b32 v43, v28, v42
	v_lshl_add_u64 v[30:31], s[0:1], 0, v[38:39]
	s_waitcnt lgkmcnt(0)
	v_add_f32_e32 v12, v42, v43
	ds_bpermute_b32 v42, v26, v12
	s_waitcnt lgkmcnt(0)
	v_add_f32_e32 v12, v12, v42
	v_fmamk_f32 v12, v12, 0x3c000000, v23
	v_mul_f32_e32 v42, 0x4f800000, v12
	v_cmp_gt_f32_e32 vcc, s3, v12
	s_waitcnt vmcnt(7)
	v_lshlrev_b32_e32 v43, 16, v68
	v_cndmask_b32_e32 v12, v12, v42, vcc
	v_sqrt_f32_e32 v42, v12
	v_and_b32_e32 v34, 0xffff0000, v68
	v_lshlrev_b32_e32 v45, 16, v69
	v_and_b32_e32 v35, 0xffff0000, v69
	v_add_u32_e32 v48, -1, v42
	v_add_u32_e32 v49, 1, v42
	v_fma_f32 v50, -v48, v42, v12
	v_fma_f32 v51, -v49, v42, v12
	v_cmp_ge_f32_e64 s[38:39], 0, v50
	v_lshlrev_b32_e32 v46, 16, v70
	v_and_b32_e32 v36, 0xffff0000, v70
	v_cndmask_b32_e64 v42, v42, v48, s[38:39]
	v_cmp_lt_f32_e64 s[38:39], 0, v51
	v_lshlrev_b32_e32 v47, 16, v71
	v_and_b32_e32 v37, 0xffff0000, v71
	v_cndmask_b32_e64 v42, v42, v49, s[38:39]
	v_mul_f32_e32 v48, 0x37800000, v42
	v_cndmask_b32_e32 v42, v42, v48, vcc
	v_cmp_class_f32_e32 vcc, v12, v24
	s_nop 1
	v_cndmask_b32_e32 v12, v42, v12, vcc
	v_div_scale_f32 v42, s[4:5], v12, v12, 1.0
	v_rcp_f32_e32 v48, v42
	v_div_scale_f32 v49, vcc, 1.0, v12, 1.0
	v_fma_f32 v50, -v42, v48, 1.0
	v_fmac_f32_e32 v48, v50, v48
	v_mul_f32_e32 v50, v49, v48
	v_fma_f32 v51, -v42, v50, v49
	v_fmac_f32_e32 v50, v51, v48
	v_fma_f32 v42, -v42, v50, v49
	v_div_fmas_f32 v42, v42, v48, v50
	v_div_fixup_f32 v12, v42, v12, 1.0
	v_mul_f32_e32 v8, v8, v12
	v_mul_f32_e32 v9, v9, v12
	v_mul_f32_e32 v10, v10, v12
	v_mul_f32_e32 v11, v11, v12
	v_mul_f32_e32 v29, v29, v12
	v_mul_f32_e32 v42, v44, v12
	v_mul_f32_e32 v40, v40, v12
	v_mul_f32_e32 v41, v41, v12
	v_mul_f32_e32 v8, v1, v8
	v_mul_f32_e32 v9, v3, v9
	v_mul_f32_e32 v10, v5, v10
	v_mul_f32_e32 v11, v7, v11
	v_mul_f32_e32 v12, v0, v29
	v_mul_f32_e32 v29, v2, v42
	v_mul_f32_e32 v40, v4, v40
	v_mul_f32_e32 v41, v6, v41
	v_mul_f32_e32 v8, v8, v34
	v_mul_f32_e32 v9, v9, v35
	v_mul_f32_e32 v10, v10, v36
	v_mul_f32_e32 v11, v11, v37
	v_mul_f32_e32 v12, v12, v43
	v_mul_f32_e32 v29, v29, v45
	v_mul_f32_e32 v34, v40, v46
	v_mul_f32_e32 v35, v41, v47
	v_cvt_pk_bf16_f32 v8, v12, v8
	v_cvt_pk_bf16_f32 v9, v29, v9
	v_cvt_pk_bf16_f32 v10, v34, v10
	v_cvt_pk_bf16_f32 v11, v35, v11
	global_store_dwordx4 v[16:17], v[8:11], off offset:1024

; #define GAS __attribute__((address_space(1)))
; __device__ __forceinline__ void readout_phase(int gw, int NGW, int lane_in, const bf16* OFW, const bf16* OBW, const bf16* HG, const float* onorm, bf16* XN) {
;     ...
;             const v4u a = __builtin_nontemporal_load((const GAS v4u*)(OFW + ho)), bq = __builtin_nontemporal_load((const GAS v4u*)(OBW + ho)), gq = __builtin_nontemporal_load((const GAS v4u*)(HG + (size_t)64 * MALL * 128 + ho));
	s_nop 0

; #define GAS __attribute__((address_space(1)))
; __device__ __forceinline__ void readout_phase(int gw, int NGW, int lane_in, const bf16* OFW, const bf16* OBW, const bf16* HG, const float* onorm, bf16* XN) {
;     ...
;             const v4u a = __builtin_nontemporal_load((const GAS v4u*)(OFW + ho)), bq = __builtin_nontemporal_load((const GAS v4u*)(OBW + ho)), gq = __builtin_nontemporal_load((const GAS v4u*)(HG + (size_t)64 * MALL * 128 + ho));
	v_lshl_add_u64 v[34:35], s[26:27], 0, v[38:39]

; #define GAS __attribute__((address_space(1)))
; __device__ __forceinline__ unsigned pk2(float lo, float hi) { return pg8::cvt_pk_bf16(lo, hi); }
; __device__ __forceinline__ void readout_phase(int gw, int NGW, int lane_in, const bf16* OFW, const bf16* OBW, const bf16* HG, const float* onorm, bf16* XN) {
;     ...
;             for (int q = 0; q < 4; ++q) { o[2 * q] = bf2f(a[q] & 0xffffu) + bf2f(bq[q] & 0xffffu); o[2 * q + 1] = bf2f(a[q] >> 16) + bf2f(bq[q] >> 16); sg[2 * q] = bf2f(gq[q] & 0xffffu); sg[2 * q + 1] = bf2f(gq[q] >> 16); }
;             float ss = 0.f;
; #pragma unroll
;             for (int e = 0; e < 8; ++e) ss += o[e] * o[e];
;             ss += __shfl_xor(ss, 1); ss += __shfl_xor(ss, 2); ss += __shfl_xor(ss, 4); ss += __shfl_xor(ss, 8);
;             const float rs = 1.f / sqrtf(ss * (1.f / 128.f) + EPS);
;             v4u w;
; #pragma unroll
;             for (int q = 0; q < 4; ++q) w[q] = pk2(o[2 * q] * rs * gn[2 * q] * sg[2 * q], o[2 * q + 1] * rs * gn[2 * q + 1] * sg[2 * q + 1]);
;             *(GAS v4u*)(XN + (size_t)r * 2048 + col) = w; }
	s_waitcnt vmcnt(7)
	v_lshlrev_b32_e32 v12, 16, v72
	s_waitcnt vmcnt(6)
	v_lshlrev_b32_e32 v29, 16, v76
	v_and_b32_e32 v30, 0xffff0000, v76
	v_and_b32_e32 v8, 0xffff0000, v72
	v_add_f32_e32 v29, v29, v12
	v_lshlrev_b32_e32 v38, 16, v73
	v_lshlrev_b32_e32 v39, 16, v77
	v_add_f32_e32 v8, v30, v8
	v_mul_f32_e32 v12, v29, v29
	v_and_b32_e32 v31, 0xffff0000, v77
	v_and_b32_e32 v9, 0xffff0000, v73
	v_add_f32_e32 v44, v39, v38
	v_fmac_f32_e32 v12, v8, v8
	v_lshlrev_b32_e32 v40, 16, v74
	v_lshlrev_b32_e32 v41, 16, v78
	v_add_f32_e32 v9, v31, v9
	v_fmac_f32_e32 v12, v44, v44
	v_and_b32_e32 v32, 0xffff0000, v78
	v_and_b32_e32 v10, 0xffff0000, v74
	v_add_f32_e32 v40, v41, v40
	v_fmac_f32_e32 v12, v9, v9
	v_lshlrev_b32_e32 v42, 16, v75
	v_lshlrev_b32_e32 v43, 16, v79
	v_add_f32_e32 v10, v32, v10
	v_fmac_f32_e32 v12, v40, v40
	v_and_b32_e32 v33, 0xffff0000, v79
	v_and_b32_e32 v11, 0xffff0000, v75
	v_add_f32_e32 v41, v43, v42
	v_fmac_f32_e32 v12, v10, v10
	v_add_f32_e32 v11, v33, v11
	v_fmac_f32_e32 v12, v41, v41
	v_fmac_f32_e32 v12, v11, v11
	ds_bpermute_b32 v30, v25, v12
	s_waitcnt vmcnt(5)
	v_lshlrev_b32_e32 v45, 16, v81
	v_and_b32_e32 v35, 0xffff0000, v81
	v_lshlrev_b32_e32 v46, 16, v82
	v_and_b32_e32 v36, 0xffff0000, v82
	s_waitcnt lgkmcnt(0)
	v_add_f32_e32 v30, v12, v30
	ds_bpermute_b32 v31, v27, v30
	v_add_u32_e32 v12, s28, v21
	v_lshlrev_b64 v[38:39], 8, v[12:13]
	v_lshlrev_b32_e32 v47, 16, v83
	v_and_b32_e32 v37, 0xffff0000, v83
	s_waitcnt lgkmcnt(0)
	v_add_f32_e32 v42, v30, v31
	ds_bpermute_b32 v43, v28, v42
	v_or_b32_e32 v38, v38, v22
	v_lshl_add_u64 v[30:31], s[0:1], 0, v[38:39]
	v_lshl_add_u64 v[32:33], s[20:21], 0, v[38:39]
	s_waitcnt lgkmcnt(0)
	v_add_f32_e32 v12, v42, v43
	ds_bpermute_b32 v42, v26, v12
	v_lshlrev_b32_e32 v43, 16, v80
	v_and_b32_e32 v34, 0xffff0000, v80
	s_waitcnt lgkmcnt(0)
	v_add_f32_e32 v12, v12, v42
	v_fmamk_f32 v12, v12, 0x3c000000, v23
	v_mul_f32_e32 v42, 0x4f800000, v12
	v_cmp_gt_f32_e32 vcc, s3, v12
	s_nop 1
	v_cndmask_b32_e32 v12, v12, v42, vcc
	v_sqrt_f32_e32 v42, v12
	s_nop 0
	v_add_u32_e32 v48, -1, v42
	v_add_u32_e32 v49, 1, v42
	v_fma_f32 v50, -v48, v42, v12
	v_fma_f32 v51, -v49, v42, v12
	v_cmp_ge_f32_e64 s[38:39], 0, v50
	s_nop 1
	v_cndmask_b32_e64 v42, v42, v48, s[38:39]
	v_cmp_lt_f32_e64 s[38:39], 0, v51
	s_nop 1
	v_cndmask_b32_e64 v42, v42, v49, s[38:39]
	v_mul_f32_e32 v48, 0x37800000, v42
	v_cndmask_b32_e32 v42, v42, v48, vcc
	v_cmp_class_f32_e32 vcc, v12, v24
	s_nop 1
	v_cndmask_b32_e32 v12, v42, v12, vcc
	v_div_scale_f32 v42, s[4:5], v12, v12, 1.0
	v_rcp_f32_e32 v48, v42
	v_div_scale_f32 v49, vcc, 1.0, v12, 1.0
	v_fma_f32 v50, -v42, v48, 1.0
	v_fmac_f32_e32 v48, v50, v48
	v_mul_f32_e32 v50, v49, v48
	v_fma_f32 v51, -v42, v50, v49
	v_fmac_f32_e32 v50, v51, v48
	v_fma_f32 v42, -v42, v50, v49
	v_div_fmas_f32 v42, v42, v48, v50
	v_div_fixup_f32 v12, v42, v12, 1.0
	v_mul_f32_e32 v8, v8, v12
	v_mul_f32_e32 v9, v9, v12
	v_mul_f32_e32 v10, v10, v12
	v_mul_f32_e32 v11, v11, v12
	v_mul_f32_e32 v29, v29, v12
	v_mul_f32_e32 v42, v44, v12
	v_mul_f32_e32 v40, v40, v12
	v_mul_f32_e32 v41, v41, v12
	v_mul_f32_e32 v8, v1, v8
	v_mul_f32_e32 v9, v3, v9
	v_mul_f32_e32 v10, v5, v10
	v_mul_f32_e32 v11, v7, v11
	v_mul_f32_e32 v12, v0, v29
	v_mul_f32_e32 v29, v2, v42
	v_mul_f32_e32 v40, v4, v40
	v_mul_f32_e32 v41, v6, v41
	v_mul_f32_e32 v8, v8, v34
	v_mul_f32_e32 v9, v9, v35
	v_mul_f32_e32 v10, v10, v36
	v_mul_f32_e32 v11, v11, v37
	v_mul_f32_e32 v12, v12, v43
	v_mul_f32_e32 v29, v29, v45
	v_mul_f32_e32 v34, v40, v46
	v_mul_f32_e32 v35, v41, v47
	v_cvt_pk_bf16_f32 v8, v12, v8
	v_cvt_pk_bf16_f32 v9, v29, v9
	v_cvt_pk_bf16_f32 v10, v34, v10
	v_cvt_pk_bf16_f32 v11, v35, v11
	global_store_dwordx4 v[16:17], v[8:11], off offset:2048

; #define GAS __attribute__((address_space(1)))
; __device__ __forceinline__ void readout_phase(int gw, int NGW, int lane_in, const bf16* OFW, const bf16* OBW, const bf16* HG, const float* onorm, bf16* XN) {
;     ...
;             const v4u a = __builtin_nontemporal_load((const GAS v4u*)(OFW + ho)), bq = __builtin_nontemporal_load((const GAS v4u*)(OBW + ho)), gq = __builtin_nontemporal_load((const GAS v4u*)(HG + (size_t)64 * MALL * 128 + ho));
	s_nop 0

; #define GAS __attribute__((address_space(1)))
; __device__ __forceinline__ void readout_phase(int gw, int NGW, int lane_in, const bf16* OFW, const bf16* OBW, const bf16* HG, const float* onorm, bf16* XN) {
;     ...
;             const v4u a = __builtin_nontemporal_load((const GAS v4u*)(OFW + ho)), bq = __builtin_nontemporal_load((const GAS v4u*)(OBW + ho)), gq = __builtin_nontemporal_load((const GAS v4u*)(HG + (size_t)64 * MALL * 128 + ho));
	v_lshl_add_u64 v[34:35], s[26:27], 0, v[38:39]

; #define GAS __attribute__((address_space(1)))
; __device__ __forceinline__ unsigned pk2(float lo, float hi) { return pg8::cvt_pk_bf16(lo, hi); }
; __device__ __forceinline__ void readout_phase(int gw, int NGW, int lane_in, const bf16* OFW, const bf16* OBW, const bf16* HG, const float* onorm, bf16* XN) {
;     ...
;             for (int q = 0; q < 4; ++q) { o[2 * q] = bf2f(a[q] & 0xffffu) + bf2f(bq[q] & 0xffffu); o[2 * q + 1] = bf2f(a[q] >> 16) + bf2f(bq[q] >> 16); sg[2 * q] = bf2f(gq[q] & 0xffffu); sg[2 * q + 1] = bf2f(gq[q] >> 16); }
;             float ss = 0.f;
; #pragma unroll
;             for (int e = 0; e < 8; ++e) ss += o[e] * o[e];
;             ss += __shfl_xor(ss, 1); ss += __shfl_xor(ss, 2); ss += __shfl_xor(ss, 4); ss += __shfl_xor(ss, 8);
;             const float rs = 1.f / sqrtf(ss * (1.f / 128.f) + EPS);
;             v4u w;
; #pragma unroll
;             for (int q = 0; q < 4; ++q) w[q] = pk2(o[2 * q] * rs * gn[2 * q] * sg[2 * q], o[2 * q + 1] * rs * gn[2 * q + 1] * sg[2 * q + 1]);
;             *(GAS v4u*)(XN + (size_t)r * 2048 + col) = w; }
	s_waitcnt vmcnt(5)
	v_lshlrev_b32_e32 v12, 16, v84
	s_waitcnt vmcnt(4)
	v_lshlrev_b32_e32 v29, 16, v88
	v_and_b32_e32 v30, 0xffff0000, v88
	v_and_b32_e32 v8, 0xffff0000, v84
	v_lshlrev_b32_e32 v40, 16, v86
	v_lshlrev_b32_e32 v41, 16, v90
	v_and_b32_e32 v32, 0xffff0000, v90
	v_and_b32_e32 v10, 0xffff0000, v86
	v_add_f32_e32 v12, v29, v12
	v_lshlrev_b32_e32 v38, 16, v85
	v_lshlrev_b32_e32 v39, 16, v89
	v_add_f32_e32 v8, v30, v8
	v_add_f32_e32 v10, v32, v10
	v_mul_f32_e32 v32, v12, v12
	v_and_b32_e32 v31, 0xffff0000, v89
	v_and_b32_e32 v9, 0xffff0000, v85
	v_add_f32_e32 v29, v39, v38
	v_fmac_f32_e32 v32, v8, v8
	v_add_f32_e32 v9, v31, v9
	v_fmac_f32_e32 v32, v29, v29
	v_add_f32_e32 v30, v41, v40
	v_fmac_f32_e32 v32, v9, v9
	v_lshlrev_b32_e32 v42, 16, v87
	v_lshlrev_b32_e32 v43, 16, v91
	v_fmac_f32_e32 v32, v30, v30
	v_and_b32_e32 v33, 0xffff0000, v91
	v_and_b32_e32 v11, 0xffff0000, v87
	v_add_f32_e32 v31, v43, v42
	v_fmac_f32_e32 v32, v10, v10
	v_add_f32_e32 v11, v33, v11
	v_fmac_f32_e32 v32, v31, v31
	v_fmac_f32_e32 v32, v11, v11
	ds_bpermute_b32 v25, v25, v32
	s_waitcnt vmcnt(3)
	v_and_b32_e32 v33, 0xffff0000, v93
	s_waitcnt lgkmcnt(0)
	v_add_f32_e32 v25, v32, v25
	ds_bpermute_b32 v27, v27, v25
	v_lshlrev_b32_e32 v32, 16, v93
	v_and_b32_e32 v35, 0xffff0000, v94
	s_waitcnt lgkmcnt(0)
	v_add_f32_e32 v25, v25, v27
	ds_bpermute_b32 v27, v28, v25
	v_and_b32_e32 v28, 0xffff0000, v92
	s_waitcnt lgkmcnt(0)
	v_add_f32_e32 v25, v25, v27
	ds_bpermute_b32 v26, v26, v25
	v_lshlrev_b32_e32 v27, 16, v92
	v_lshlrev_b32_e32 v34, 16, v94
	v_lshlrev_b32_e32 v36, 16, v95
	v_and_b32_e32 v37, 0xffff0000, v95
	s_waitcnt lgkmcnt(0)
	v_add_f32_e32 v25, v25, v26
	v_fmamk_f32 v25, v25, 0x3c000000, v23
	v_mul_f32_e32 v26, 0x4f800000, v25
	v_cmp_gt_f32_e32 vcc, s3, v25
	s_nop 1
	v_cndmask_b32_e32 v25, v25, v26, vcc
	v_sqrt_f32_e32 v26, v25
	s_nop 0
	v_add_u32_e32 v38, -1, v26
	v_add_u32_e32 v39, 1, v26
	v_fma_f32 v40, -v38, v26, v25
	v_fma_f32 v41, -v39, v26, v25
	v_cmp_ge_f32_e64 s[38:39], 0, v40
	s_nop 1
	v_cndmask_b32_e64 v26, v26, v38, s[38:39]
	v_cmp_lt_f32_e64 s[38:39], 0, v41
	s_nop 1
	v_cndmask_b32_e64 v26, v26, v39, s[38:39]
	v_mul_f32_e32 v38, 0x37800000, v26
	v_cndmask_b32_e32 v26, v26, v38, vcc
	v_cmp_class_f32_e32 vcc, v25, v24
	s_nop 1
	v_cndmask_b32_e32 v25, v26, v25, vcc
	v_div_scale_f32 v26, s[4:5], v25, v25, 1.0
	v_rcp_f32_e32 v38, v26
	v_div_scale_f32 v39, vcc, 1.0, v25, 1.0
	v_fma_f32 v40, -v26, v38, 1.0
	v_fmac_f32_e32 v38, v40, v38
	v_mul_f32_e32 v40, v39, v38
	v_fma_f32 v41, -v26, v40, v39
	v_fmac_f32_e32 v40, v41, v38
	v_fma_f32 v26, -v26, v40, v39
	v_div_fmas_f32 v26, v26, v38, v40
	v_div_fixup_f32 v25, v26, v25, 1.0
	v_mul_f32_e32 v8, v8, v25
	v_mul_f32_e32 v9, v9, v25
	v_mul_f32_e32 v10, v10, v25
	v_mul_f32_e32 v11, v11, v25
	v_mul_f32_e32 v12, v12, v25
	v_mul_f32_e32 v26, v29, v25
	v_mul_f32_e32 v29, v30, v25
	v_mul_f32_e32 v30, v31, v25
	v_mul_f32_e32 v8, v1, v8
	v_mul_f32_e32 v9, v3, v9
	v_mul_f32_e32 v10, v5, v10
	v_mul_f32_e32 v11, v7, v11
	v_mul_f32_e32 v12, v0, v12
	v_mul_f32_e32 v25, v2, v26
	v_mul_f32_e32 v26, v4, v29
	v_mul_f32_e32 v29, v6, v30
	v_mul_f32_e32 v8, v8, v28
	v_mul_f32_e32 v9, v9, v33
	v_mul_f32_e32 v10, v10, v35
	v_mul_f32_e32 v11, v11, v37
	v_mul_f32_e32 v12, v12, v27
	v_mul_f32_e32 v25, v25, v32
	v_mul_f32_e32 v26, v26, v34
	v_mul_f32_e32 v27, v29, v36
	v_cvt_pk_bf16_f32 v8, v12, v8
	v_cvt_pk_bf16_f32 v9, v25, v9
	v_cvt_pk_bf16_f32 v10, v26, v10
	v_cvt_pk_bf16_f32 v11, v27, v11
	global_store_dwordx4 v[16:17], v[8:11], off offset:3072
